# GLA scan: 16-byte chunk index of the 144-byte-stride LDS images XOR-swizzled by row group so the ds_read_b128 lane groups are bank-conflict free
# speedup vs baseline: 1.0142x; 1.0023x over previous
.LBB0_243:
	s_or_b64 exec, exec, s[10:11]
	s_add_i32 s10, 0, 0x19800
	s_cmpk_lg_i32 s26, 0x7f3
	s_cselect_b32 s11, s24, 31
	s_add_i32 s28, s11, s6
	s_ashr_i32 s29, s28, 31
	s_lshl_b64 s[52:53], s[28:29], 15
	v_lshlrev_b32_e32 v8, 1, v108
	s_add_u32 s54, s13, s52
	v_and_b32_e32 v8, 0x7e, v8
	v_ashrrev_i32_e32 v9, 2, v108
	s_addc_u32 s55, s14, s53
	s_waitcnt vmcnt(6)
	v_lshlrev_b32_e32 v0, 16, v131
	s_waitcnt vmcnt(4)
	v_lshlrev_b32_e32 v1, 16, v133
	s_waitcnt vmcnt(2)
	v_lshlrev_b32_e32 v2, 16, v135
	s_waitcnt vmcnt(0)
	v_lshlrev_b32_e32 v3, 16, v137
	v_lshrrev_b32_e32 v4, 16, v130
	v_lshrrev_b32_e32 v5, 16, v132
	v_mul_u32_u24_e32 v8, 0x90, v8
	v_and_b32_e32 v9, -16, v9
	v_lshlrev_b32_e32 v208, 1, v108
	v_and_b32_e32 v208, 14, v208
	v_add_u32_e32 v208, 4, v208
	v_lshlrev_b32_e32 v208, 1, v208
	v_and_b32_e32 v208, 16, v208
	v_xor_b32_e32 v9, v9, v208
	s_add_u32 s52, s15, s52
	v_add_u32_e32 v12, 0x2000, v106
	v_add_u32_e32 v20, 0x4000, v106
	v_add_u32_e32 v28, 0x6000, v106
	v_and_or_b32 v0, v130, s35, v0
	v_and_or_b32 v1, v132, s35, v1
	v_and_or_b32 v2, v134, s35, v2
	v_and_or_b32 v3, v136, s35, v3
	v_and_or_b32 v4, v131, s88, v4
	v_and_or_b32 v5, v133, s88, v5
	v_lshrrev_b32_e32 v6, 16, v134
	v_lshrrev_b32_e32 v7, 16, v136
	v_add3_u32 v8, s10, v8, v9
	s_addc_u32 s53, s16, s53
	v_ashrrev_i32_e32 v13, 31, v12
	v_ashrrev_i32_e32 v21, 31, v20
	v_ashrrev_i32_e32 v29, 31, v28
	v_and_or_b32 v6, v135, s88, v6
	v_and_or_b32 v7, v137, s88, v7
	ds_write_b128 v8, v[0:3]
	ds_write_b128 v8, v[4:7] offset:144
	v_lshl_add_u64 v[4:5], s[52:53], 0, v[106:107]
	v_lshl_add_u64 v[8:9], s[54:55], 0, v[12:13]
	v_lshl_add_u64 v[12:13], s[52:53], 0, v[12:13]
	v_lshl_add_u64 v[16:17], s[54:55], 0, v[20:21]
	v_lshl_add_u64 v[20:21], s[52:53], 0, v[20:21]
	v_lshl_add_u64 v[24:25], s[54:55], 0, v[28:29]
	v_lshl_add_u64 v[28:29], s[52:53], 0, v[28:29]
	s_lshl_b64 s[52:53], s[28:29], 13
	s_add_u32 s52, s17, s52
	s_addc_u32 s53, s18, s53
	s_lshl_b64 s[28:29], s[28:29], 11
	s_add_u32 s28, s19, s28
	v_lshl_add_u64 v[0:1], s[54:55], 0, v[106:107]
	v_lshl_add_u64 v[32:33], s[52:53], 0, v[106:107]
	s_addc_u32 s29, s20, s29
	v_and_b32_e32 v106, 63, v108
	s_lshl_b32 s11, s11, 6
	s_waitcnt lgkmcnt(0)
	s_barrier
	v_lshlrev_b32_e32 v40, 4, v106
	s_sub_i32 s47, 0x7ff, s11
	global_load_dwordx4 v[0:3], v[0:1], off
	v_and_b32_e32 v107, -8, v64
	global_load_dwordx4 v[40:43], v40, s[28:29]
	s_and_b64 s[28:29], vcc, exec
	s_cselect_b32 s11, s11, s47
	s_add_i32 s11, s11, s7
	s_mul_hi_i32 s29, s11, 0xa080
	s_mul_i32 s11, s11, 0xa080
	v_lshl_or_b32 v106, v106, 1, s23
	s_add_u32 s28, s0, s11
	v_mad_u64_u32 v[108:109], s[52:53], v107, s22, v[106:107]
	s_addc_u32 s29, s2, s29
	v_ashrrev_i32_e32 v109, 31, v108
	v_lshl_add_u64 v[110:111], v[108:109], 1, s[28:29]
	v_add_u32_e32 v108, s22, v108
	v_ashrrev_i32_e32 v109, 31, v108
	global_load_dword v130, v[110:111], off
	v_lshl_add_u64 v[110:111], v[108:109], 1, s[28:29]
	v_add_u32_e32 v108, s22, v108
	v_ashrrev_i32_e32 v109, 31, v108
	global_load_dword v131, v[110:111], off
	v_lshl_add_u64 v[110:111], v[108:109], 1, s[28:29]
	v_add_u32_e32 v108, s22, v108
	v_ashrrev_i32_e32 v109, 31, v108
	global_load_dword v132, v[110:111], off
	v_lshl_add_u64 v[110:111], v[108:109], 1, s[28:29]
	v_add_u32_e32 v108, s22, v108
	v_ashrrev_i32_e32 v109, 31, v108
	global_load_dword v133, v[110:111], off
	v_lshl_add_u64 v[110:111], v[108:109], 1, s[28:29]
	v_add_u32_e32 v108, s22, v108
	v_ashrrev_i32_e32 v109, 31, v108
	v_or_b32_e32 v64, 7, v64
	global_load_dword v134, v[110:111], off
	v_lshl_add_u64 v[110:111], v[108:109], 1, s[28:29]
	v_add_u32_e32 v108, s22, v108
	v_mad_u64_u32 v[106:107], s[52:53], v64, s22, v[106:107]
	v_ashrrev_i32_e32 v109, 31, v108
	v_ashrrev_i32_e32 v107, 31, v106
	v_lshl_add_u64 v[108:109], v[108:109], 1, s[28:29]
	v_lshl_add_u64 v[106:107], v[106:107], 1, s[28:29]
	global_load_dwordx4 v[4:7], v[4:5], off
	s_nop 0
	global_load_dwordx4 v[8:11], v[8:9], off
	s_nop 0
	global_load_dwordx4 v[12:15], v[12:13], off
	s_nop 0
	global_load_dwordx4 v[16:19], v[16:17], off
	s_nop 0
	global_load_dwordx4 v[20:23], v[20:21], off
	s_nop 0
	global_load_dwordx4 v[24:27], v[24:25], off
	s_nop 0
	global_load_dwordx4 v[28:31], v[28:29], off
	s_nop 0
	global_load_dwordx4 v[32:35], v[32:33], off
	s_nop 0
	global_load_dword v135, v[110:111], off
	global_load_dword v136, v[108:109], off
	global_load_dword v137, v[106:107], off
	v_mov_b32_e32 v64, 0
	s_cmp_lg_u32 s36, -1
	v_add_u32_e32 v106, v64, v189
	v_and_b32_e32 v64, 15, v106
	v_ashrrev_i32_e32 v140, 4, v106
	v_and_b32_e32 v106, -16, v106
	v_add_u32_e32 v208, 4, v64
	v_lshlrev_b32_e32 v208, 1, v208
	v_and_b32_e32 v208, 16, v208
	v_xor_b32_e32 v208, v106, v208
	s_cselect_b32 s11, s36, 0
	s_cmp_lg_u32 s10, -1
	v_mad_u32_u24 v109, v64, s38, v208
	s_cselect_b32 s10, s10, 0
	s_cmp_lg_u32 0, -1
	v_mul_u32_u24_e32 v107, 0x210, v64
	v_lshlrev_b32_e32 v108, 3, v140
	v_add_u32_e32 v138, s11, v109
	s_cselect_b32 s11, 0, 0
	s_cmp_lg_u32 s27, -1
	v_add3_u32 v128, v107, s11, v108
	s_cselect_b32 s11, s27, 0
	v_add_u32_e32 v114, s11, v109
	s_add_i32 s11, 0, 0x22400
	v_or_b32_e32 v110, s4, v64
	s_cmp_lg_u32 s11, -1
	s_cselect_b32 s11, s11, 0
	v_mul_lo_u32 v107, v110, s38
	v_add_u32_e32 v139, s11, v106
	v_add3_u32 v115, v208, s10, v107
	ds_read_b64 v[106:107], v128 offset:0
	ds_read_b64 v[108:109], v128 offset:32
	ds_read_b64 v[110:111], v128 offset:0x2100
	ds_read_b64 v[112:113], v128 offset:0x2120
	ds_read_b64 v[116:117], v128 offset:0x4200
	ds_read_b64 v[118:119], v128 offset:0x4220
	ds_read_b64 v[120:121], v128 offset:0x6300
	ds_read_b64 v[122:123], v128 offset:0x6320
	ds_read_b64 v[124:125], v128 offset:64
	ds_read_b64 v[126:127], v128 offset:0x60
	ds_read_b64 v[142:143], v128 offset:0x2140
	ds_read_b64 v[144:145], v128 offset:0x2160
	ds_read_b64 v[154:155], v128 offset:0x4240
	ds_read_b64 v[156:157], v128 offset:0x4260
	ds_read_b64 v[158:159], v128 offset:0x6340
	ds_read_b64 v[160:161], v128 offset:0x6360
	s_waitcnt lgkmcnt(0)
	v_cvt_pk_bf16_f32 v162, v102, v103
	v_cvt_pk_bf16_f32 v163, v104, v105
	v_cvt_pk_bf16_f32 v164, v98, v99
	v_cvt_pk_bf16_f32 v165, v100, v101
	v_cvt_pk_bf16_f32 v166, v94, v95
	v_cvt_pk_bf16_f32 v167, v96, v97
	v_cvt_pk_bf16_f32 v168, v90, v91
	v_cvt_pk_bf16_f32 v169, v92, v93
	v_mfma_f32_16x16x32_bf16 v[106:109], v[106:109], v[162:165], 0
	v_cvt_pk_bf16_f32 v178, v74, v75
	v_cvt_pk_bf16_f32 v179, v76, v77
	v_cvt_pk_bf16_f32 v180, v66, v67
	v_mfma_f32_16x16x32_bf16 v[110:113], v[110:113], v[162:165], 0
	v_cvt_pk_bf16_f32 v181, v68, v69
	v_cvt_pk_bf16_f32 v192, v60, v61
	v_cvt_pk_bf16_f32 v193, v62, v63
	v_mfma_f32_16x16x32_bf16 v[116:119], v[116:119], v[162:165], 0
	v_cvt_pk_bf16_f32 v194, v56, v57
	v_cvt_pk_bf16_f32 v195, v58, v59
	v_mfma_f32_16x16x32_bf16 v[106:109], v[124:127], v[166:169], v[106:109]
	ds_read_b64 v[124:125], v128 offset:0x80
	ds_read_b64 v[126:127], v128 offset:0xa0
	v_mfma_f32_16x16x32_bf16 v[120:123], v[120:123], v[162:165], 0
	v_mfma_f32_16x16x32_bf16 v[110:113], v[142:145], v[166:169], v[110:113]
	ds_read_b64 v[142:143], v128 offset:0x2180
	ds_read_b64 v[144:145], v128 offset:0x21a0
	v_mfma_f32_16x16x32_bf16 v[116:119], v[154:157], v[166:169], v[116:119]
	ds_read_b64 v[154:155], v128 offset:0x4280
	ds_read_b64 v[156:157], v128 offset:0x42a0
	v_mfma_f32_16x16x32_bf16 v[120:123], v[158:161], v[166:169], v[120:123]
	ds_read_b64 v[158:159], v128 offset:0x6380
	ds_read_b64 v[160:161], v128 offset:0x63a0
	ds_read_b64 v[162:163], v128 offset:0xc0
	ds_read_b64 v[164:165], v128 offset:0xe0
	ds_read_b64 v[166:167], v128 offset:0x21c0
	ds_read_b64 v[168:169], v128 offset:0x21e0
	ds_read_b64 v[170:171], v128 offset:0x42c0
	ds_read_b64 v[172:173], v128 offset:0x42e0
	ds_read_b64 v[174:175], v128 offset:0x63c0
	ds_read_b64 v[176:177], v128 offset:0x63e0
	s_waitcnt lgkmcnt(0)
	v_mfma_f32_16x16x32_bf16 v[106:109], v[124:127], v[178:181], v[106:109]
	ds_read_b64 v[124:125], v128 offset:0x100
	ds_read_b64 v[126:127], v128 offset:0x120
	v_mfma_f32_16x16x32_bf16 v[110:113], v[142:145], v[178:181], v[110:113]
	ds_read_b64 v[142:143], v128 offset:0x2200
	ds_read_b64 v[144:145], v128 offset:0x2220
	v_mfma_f32_16x16x32_bf16 v[116:119], v[154:157], v[178:181], v[116:119]
	ds_read_b64 v[154:155], v128 offset:0x4300
	ds_read_b64 v[156:157], v128 offset:0x4320
	v_mfma_f32_16x16x32_bf16 v[120:123], v[158:161], v[178:181], v[120:123]
	ds_read_b64 v[158:159], v128 offset:0x6400
	ds_read_b64 v[160:161], v128 offset:0x6420
	v_cvt_pk_bf16_f32 v178, v86, v87
	v_mfma_f32_16x16x32_bf16 v[106:109], v[162:165], v[192:195], v[106:109]
	ds_read_b64 v[162:163], v128 offset:0x140
	ds_read_b64 v[164:165], v128 offset:0x160
	v_cvt_pk_bf16_f32 v179, v88, v89
	v_mfma_f32_16x16x32_bf16 v[110:113], v[166:169], v[192:195], v[110:113]
	ds_read_b64 v[166:167], v128 offset:0x2240
	ds_read_b64 v[168:169], v128 offset:0x2260
	v_cvt_pk_bf16_f32 v180, v82, v83
	v_mfma_f32_16x16x32_bf16 v[116:119], v[170:173], v[192:195], v[116:119]
	ds_read_b64 v[170:171], v128 offset:0x4340
	ds_read_b64 v[172:173], v128 offset:0x4360
	v_cvt_pk_bf16_f32 v181, v84, v85
	v_mfma_f32_16x16x32_bf16 v[120:123], v[174:177], v[192:195], v[120:123]
	ds_read_b64 v[174:175], v128 offset:0x6440
	ds_read_b64 v[176:177], v128 offset:0x6460
	s_waitcnt lgkmcnt(0)
	v_cvt_pk_bf16_f32 v192, v78, v79
	v_cvt_pk_bf16_f32 v193, v80, v81
	v_cvt_pk_bf16_f32 v194, v70, v71
	v_cvt_pk_bf16_f32 v195, v72, v73
	v_mfma_f32_16x16x32_bf16 v[106:109], v[124:127], v[178:181], v[106:109]
	ds_read_b64 v[124:125], v128 offset:0x180
	ds_read_b64 v[126:127], v128 offset:0x1a0
	v_mfma_f32_16x16x32_bf16 v[110:113], v[142:145], v[178:181], v[110:113]
	ds_read_b64 v[142:143], v128 offset:0x2280
	ds_read_b64 v[144:145], v128 offset:0x22a0
	v_mfma_f32_16x16x32_bf16 v[116:119], v[154:157], v[178:181], v[116:119]
	ds_read_b64 v[154:155], v128 offset:0x4380
	ds_read_b64 v[156:157], v128 offset:0x43a0
	v_mfma_f32_16x16x32_bf16 v[120:123], v[158:161], v[178:181], v[120:123]
	ds_read_b64 v[158:159], v128 offset:0x6480
	ds_read_b64 v[160:161], v128 offset:0x64a0
	v_cvt_pk_bf16_f32 v178, v48, v49
	v_mfma_f32_16x16x32_bf16 v[106:109], v[162:165], v[192:195], v[106:109]
	ds_read_b64 v[162:163], v128 offset:0x1c0
	ds_read_b64 v[164:165], v128 offset:0x1e0
	v_cvt_pk_bf16_f32 v179, v50, v51
	v_mfma_f32_16x16x32_bf16 v[110:113], v[166:169], v[192:195], v[110:113]
	ds_read_b64 v[166:167], v128 offset:0x22c0
	ds_read_b64 v[168:169], v128 offset:0x22e0
	v_cvt_pk_bf16_f32 v180, v44, v45
	v_mfma_f32_16x16x32_bf16 v[116:119], v[170:173], v[192:195], v[116:119]
	ds_read_b64 v[170:171], v128 offset:0x43c0
	ds_read_b64 v[172:173], v128 offset:0x43e0
	v_cvt_pk_bf16_f32 v181, v46, v47
	v_mfma_f32_16x16x32_bf16 v[120:123], v[174:177], v[192:195], v[120:123]
	ds_read_b64 v[174:175], v128 offset:0x64c0
	ds_read_b64 v[176:177], v128 offset:0x64e0
	s_waitcnt lgkmcnt(0)
	v_cvt_pk_bf16_f32 v192, v36, v37
	v_cvt_pk_bf16_f32 v193, v38, v39
	v_cvt_pk_bf16_f32 v194, v52, v53
	v_cvt_pk_bf16_f32 v195, v54, v55
	v_mfma_f32_16x16x32_bf16 v[110:113], v[142:145], v[178:181], v[110:113]
	v_mfma_f32_16x16x32_bf16 v[106:109], v[124:127], v[178:181], v[106:109]
	v_mfma_f32_16x16x32_bf16 v[142:145], v[166:169], v[192:195], v[110:113]
	ds_read_b128 v[110:113], v115 offset:0
	v_mfma_f32_16x16x32_bf16 v[124:127], v[162:165], v[192:195], v[106:109]
	ds_read_b128 v[106:109], v115 offset:64
	v_mfma_f32_16x16x32_bf16 v[116:119], v[154:157], v[178:181], v[116:119]
	ds_read_b128 v[154:157], v114 offset:0
	v_mfma_f32_16x16x32_bf16 v[120:123], v[158:161], v[178:181], v[120:123]
	ds_read_b128 v[158:161], v114 offset:64
	ds_read_b128 v[162:165], v114 offset:0x900
	ds_read_b128 v[166:169], v114 offset:0x940
	v_mfma_f32_16x16x32_bf16 v[116:119], v[170:173], v[192:195], v[116:119]
	ds_read_b128 v[170:173], v114 offset:0x1200
	v_mfma_f32_16x16x32_bf16 v[120:123], v[174:177], v[192:195], v[120:123]
	ds_read_b128 v[174:177], v114 offset:0x1240
	ds_read_b128 v[178:181], v114 offset:0x1b00
	ds_read_b128 v[192:195], v114 offset:0x1b40
	s_waitcnt lgkmcnt(0)
	s_nop 0
	v_mfma_f32_16x16x32_bf16 v[124:127], v[154:157], v[110:113], v[124:127]
	v_mfma_f32_16x16x32_bf16 v[142:145], v[162:165], v[110:113], v[142:145]
	v_mfma_f32_16x16x32_bf16 v[114:117], v[170:173], v[110:113], v[116:119]
	v_mfma_f32_16x16x32_bf16 v[154:157], v[178:181], v[110:113], v[120:123]
	v_mfma_f32_16x16x32_bf16 v[126:129], v[158:161], v[106:109], v[124:127]
	v_mfma_f32_16x16x32_bf16 v[122:125], v[166:169], v[106:109], v[142:145]
	ds_read_b128 v[142:145], v138 offset:0
	v_mfma_f32_16x16x32_bf16 v[118:121], v[174:177], v[106:109], v[114:117]
	v_mfma_f32_16x16x32_bf16 v[114:117], v[192:195], v[106:109], v[154:157]
	ds_read_b128 v[154:157], v138 offset:64
	ds_read_b128 v[158:161], v138 offset:0x900
	ds_read_b128 v[162:165], v138 offset:0x940
	ds_read_b128 v[166:169], v138 offset:0x1200
	ds_read_b128 v[170:173], v138 offset:0x1240
	ds_read_b128 v[174:177], v138 offset:0x1b00
	ds_read_b128 v[178:181], v138 offset:0x1b40
	ds_read_b128 v[192:195], v139 offset:0
	ds_read_b128 v[196:199], v139 offset:64
	ds_read_b128 v[200:203], v139 offset:0x80
	ds_read_b128 v[204:207], v139 offset:0xc0
	s_waitcnt lgkmcnt(0)
	s_nop 0
	v_mul_f32_e64 v104, v104, v194
	v_mul_f32_e64 v105, v105, v195
	v_pk_mul_f32 v[102:103], v[102:103], v[192:193]
	v_pk_mul_f32 v[100:101], v[100:101], v[198:199]
	v_pk_mul_f32 v[98:99], v[98:99], v[196:197]
	v_mfma_f32_16x16x32_bf16 v[102:105], v[142:145], v[110:113], v[102:105]
	v_mul_f32_e64 v96, v96, v202
	v_mul_f32_e64 v97, v97, v203
	v_pk_mul_f32 v[94:95], v[94:95], v[200:201]
	ds_read_b128 v[142:145], v138 offset:0x2400
	v_mfma_f32_16x16x32_bf16 v[98:101], v[158:161], v[110:113], v[98:101]
	v_mul_f32_e64 v92, v92, v206
	v_mul_f32_e64 v93, v93, v207
	v_pk_mul_f32 v[90:91], v[90:91], v[204:205]
	v_mfma_f32_16x16x32_bf16 v[94:97], v[166:169], v[110:113], v[94:97]
	v_mfma_f32_16x16x32_bf16 v[102:105], v[154:157], v[106:109], v[102:105]
	ds_read_b128 v[154:157], v138 offset:0x2440
	ds_read_b128 v[158:161], v138 offset:0x2d00
	v_mfma_f32_16x16x32_bf16 v[90:93], v[174:177], v[110:113], v[90:93]
	v_mfma_f32_16x16x32_bf16 v[98:101], v[162:165], v[106:109], v[98:101]
	ds_read_b128 v[162:165], v138 offset:0x2d40
	ds_read_b128 v[166:169], v138 offset:0x3600
	v_mfma_f32_16x16x32_bf16 v[94:97], v[170:173], v[106:109], v[94:97]
	ds_read_b128 v[170:173], v138 offset:0x3640
	ds_read_b128 v[174:177], v138 offset:0x3f00
	v_mfma_f32_16x16x32_bf16 v[90:93], v[178:181], v[106:109], v[90:93]
	ds_read_b128 v[178:181], v138 offset:0x3f40
	ds_read_b128 v[192:195], v139 offset:0x100
	ds_read_b128 v[196:199], v139 offset:0x140
	ds_read_b128 v[200:203], v139 offset:0x180
	ds_read_b128 v[204:207], v139 offset:0x1c0
	s_waitcnt lgkmcnt(0)
	s_nop 0
	v_mul_f32_e64 v76, v76, v194
	v_mul_f32_e64 v77, v77, v195
	v_pk_mul_f32 v[74:75], v[74:75], v[192:193]
	v_lshlrev_b32_e32 v64, 1, v64
	v_pk_mul_f32 v[68:69], v[68:69], v[198:199]
	v_mfma_f32_16x16x32_bf16 v[74:77], v[142:145], v[110:113], v[74:77]
	v_lshlrev_b32_e32 v142, 2, v140
	v_add_u32_e32 v144, s26, v142
	v_sub_u32_e32 v145, s25, v142
	v_lshl_add_u64 v[140:141], s[8:9], 0, v[64:65]
	v_cvt_pk_bf16_f32 v64, v126, s0
	v_subrev_u32_e32 v126, 51, v144
	v_add_u32_e32 v142, 0x7ff, v145
	v_cndmask_b32_e32 v126, v142, v126, vcc
	v_add_u32_e32 v142, s7, v126
	v_ashrrev_i32_e32 v143, 31, v142
	v_lshlrev_b64 v[142:143], 12, v[142:143]
	v_lshl_add_u64 v[142:143], v[140:141], 0, v[142:143]
	global_store_short v[142:143], v64, off
	v_cvt_pk_bf16_f32 v64, v127, s0
	v_subrev_u32_e32 v126, 50, v144
	v_add_u32_e32 v127, 0x7fe, v145
	v_cndmask_b32_e32 v126, v127, v126, vcc
	v_add_u32_e32 v126, s7, v126
	v_ashrrev_i32_e32 v127, 31, v126
	v_lshlrev_b64 v[126:127], 12, v[126:127]
	v_lshl_add_u64 v[126:127], v[140:141], 0, v[126:127]
	global_store_short v[126:127], v64, off
	v_subrev_u32_e32 v126, 49, v144
	v_add_u32_e32 v127, 0x7fd, v145
	v_cndmask_b32_e32 v126, v127, v126, vcc
	v_add_u32_e32 v126, s7, v126
	v_ashrrev_i32_e32 v127, 31, v126
	v_lshlrev_b64 v[126:127], 12, v[126:127]
	v_cvt_pk_bf16_f32 v64, v128, s0
	v_lshl_add_u64 v[126:127], v[140:141], 0, v[126:127]
	global_store_short v[126:127], v64, off
	v_subrev_u32_e32 v126, 48, v144
	v_add_u32_e32 v127, 0x7fc, v145
	v_cndmask_b32_e32 v126, v127, v126, vcc
	v_add_u32_e32 v126, s7, v126
	v_ashrrev_i32_e32 v127, 31, v126
	v_lshlrev_b64 v[126:127], 12, v[126:127]
	v_cvt_pk_bf16_f32 v64, v129, s0
	v_lshl_add_u64 v[126:127], v[140:141], 0, v[126:127]
	global_store_short v[126:127], v64, off
	v_cvt_pk_bf16_f32 v64, v122, s0
	v_subrev_u32_e32 v122, 35, v144
	v_add_u32_e32 v126, 0x7ef, v145
	v_cndmask_b32_e32 v122, v126, v122, vcc
	v_add_u32_e32 v126, s7, v122
	v_ashrrev_i32_e32 v127, 31, v126
	v_lshlrev_b64 v[126:127], 12, v[126:127]
	v_lshl_add_u64 v[126:127], v[140:141], 0, v[126:127]
	global_store_short v[126:127], v64, off
	v_cvt_pk_bf16_f32 v64, v123, s0
	v_subrev_u32_e32 v122, 34, v144
	v_add_u32_e32 v123, 0x7ee, v145
	v_cndmask_b32_e32 v122, v123, v122, vcc
	v_add_u32_e32 v122, s7, v122
	v_ashrrev_i32_e32 v123, 31, v122
	v_lshlrev_b64 v[122:123], 12, v[122:123]
	v_lshl_add_u64 v[122:123], v[140:141], 0, v[122:123]
	global_store_short v[122:123], v64, off
	v_subrev_u32_e32 v122, 33, v144
	v_add_u32_e32 v123, 0x7ed, v145
	v_cndmask_b32_e32 v122, v123, v122, vcc
	v_add_u32_e32 v122, s7, v122
	v_ashrrev_i32_e32 v123, 31, v122
	v_lshlrev_b64 v[122:123], 12, v[122:123]
	v_cvt_pk_bf16_f32 v64, v124, s0
	v_lshl_add_u64 v[122:123], v[140:141], 0, v[122:123]
	global_store_short v[122:123], v64, off
	v_subrev_u32_e32 v122, 32, v144
	v_add_u32_e32 v123, 0x7ec, v145
	v_cndmask_b32_e32 v122, v123, v122, vcc
	v_add_u32_e32 v122, s7, v122
	v_ashrrev_i32_e32 v123, 31, v122
	v_lshlrev_b64 v[122:123], 12, v[122:123]
	v_cvt_pk_bf16_f32 v64, v125, s0
	v_lshl_add_u64 v[122:123], v[140:141], 0, v[122:123]
	global_store_short v[122:123], v64, off
	v_cvt_pk_bf16_f32 v64, v118, s0
	v_subrev_u32_e32 v118, 19, v144
	v_add_u32_e32 v122, 0x7df, v145
	v_cndmask_b32_e32 v118, v122, v118, vcc
	v_add_u32_e32 v122, s7, v118
	v_ashrrev_i32_e32 v123, 31, v122
	v_lshlrev_b64 v[122:123], 12, v[122:123]
	v_lshl_add_u64 v[122:123], v[140:141], 0, v[122:123]
	global_store_short v[122:123], v64, off
	v_cvt_pk_bf16_f32 v64, v119, s0
	v_subrev_u32_e32 v118, 18, v144
	v_add_u32_e32 v119, 0x7de, v145
	v_cndmask_b32_e32 v118, v119, v118, vcc
	v_add_u32_e32 v118, s7, v118
	v_ashrrev_i32_e32 v119, 31, v118
	v_lshlrev_b64 v[118:119], 12, v[118:119]
	v_lshl_add_u64 v[118:119], v[140:141], 0, v[118:119]
	global_store_short v[118:119], v64, off
	v_subrev_u32_e32 v118, 17, v144
	v_add_u32_e32 v119, 0x7dd, v145
	v_cndmask_b32_e32 v118, v119, v118, vcc
	v_add_u32_e32 v118, s7, v118
	v_ashrrev_i32_e32 v119, 31, v118
	v_lshlrev_b64 v[118:119], 12, v[118:119]
	v_cvt_pk_bf16_f32 v64, v120, s0
	v_lshl_add_u64 v[118:119], v[140:141], 0, v[118:119]
	global_store_short v[118:119], v64, off
	v_add_u32_e32 v118, -16, v144
	v_add_u32_e32 v119, 0x7dc, v145
	v_cndmask_b32_e32 v118, v119, v118, vcc
	v_add_u32_e32 v118, s7, v118
	v_ashrrev_i32_e32 v119, 31, v118
	v_lshlrev_b64 v[118:119], 12, v[118:119]
	v_cvt_pk_bf16_f32 v64, v121, s0
	v_lshl_add_u64 v[118:119], v[140:141], 0, v[118:119]
	global_store_short v[118:119], v64, off
	v_cvt_pk_bf16_f32 v64, v114, s0
	v_add_u32_e32 v114, -3, v144
	v_add_u32_e32 v118, 0x7cf, v145
	v_cndmask_b32_e32 v114, v118, v114, vcc
	v_add_u32_e32 v118, s7, v114
	v_ashrrev_i32_e32 v119, 31, v118
	v_lshlrev_b64 v[118:119], 12, v[118:119]
	v_lshl_add_u64 v[118:119], v[140:141], 0, v[118:119]
	global_store_short v[118:119], v64, off
	v_cvt_pk_bf16_f32 v64, v115, s0
	v_add_u32_e32 v114, -2, v144
	v_add_u32_e32 v115, 0x7ce, v145
	v_cndmask_b32_e32 v114, v115, v114, vcc
	v_add_u32_e32 v114, s7, v114
	v_ashrrev_i32_e32 v115, 31, v114
	v_lshlrev_b64 v[114:115], 12, v[114:115]
	v_lshl_add_u64 v[114:115], v[140:141], 0, v[114:115]
	global_store_short v[114:115], v64, off
	v_add_u32_e32 v114, -1, v144
	v_add_u32_e32 v115, 0x7cd, v145
	v_cndmask_b32_e32 v114, v115, v114, vcc
	v_add_u32_e32 v114, s7, v114
	v_ashrrev_i32_e32 v115, 31, v114
	v_lshlrev_b64 v[114:115], 12, v[114:115]
	v_cvt_pk_bf16_f32 v64, v116, s0
	v_lshl_add_u64 v[114:115], v[140:141], 0, v[114:115]
	global_store_short v[114:115], v64, off
	v_add_u32_e32 v114, 0x7cc, v145
	v_cndmask_b32_e32 v114, v114, v144, vcc
	v_add_u32_e32 v114, s7, v114
	v_ashrrev_i32_e32 v115, 31, v114
	v_lshlrev_b64 v[114:115], 12, v[114:115]
	v_cvt_pk_bf16_f32 v64, v117, s0
	v_lshl_add_u64 v[114:115], v[140:141], 0, v[114:115]
	global_store_short v[114:115], v64, off
	ds_read_b128 v[114:117], v138 offset:0x4800
	ds_read_b128 v[118:121], v138 offset:0x4840
	ds_read_b128 v[122:125], v138 offset:0x5100
	v_pk_mul_f32 v[66:67], v[66:67], v[196:197]
	ds_read_b128 v[126:129], v138 offset:0x5140
	ds_read_b128 v[140:143], v138 offset:0x5a00
	v_pk_mul_f32 v[62:63], v[62:63], v[202:203]
	v_pk_mul_f32 v[60:61], v[60:61], v[200:201]
	v_mfma_f32_16x16x32_bf16 v[66:69], v[158:161], v[110:113], v[66:69]
	ds_read_b128 v[144:147], v138 offset:0x5a40
	v_mul_f32_e64 v58, v58, v206
	v_mul_f32_e64 v59, v59, v207
	v_pk_mul_f32 v[56:57], v[56:57], v[204:205]
	v_mfma_f32_16x16x32_bf16 v[60:63], v[166:169], v[110:113], v[60:63]
	v_mfma_f32_16x16x32_bf16 v[74:77], v[154:157], v[106:109], v[74:77]
	ds_read_b128 v[154:157], v138 offset:0x6300
	ds_read_b128 v[158:161], v138 offset:0x6340
	v_mfma_f32_16x16x32_bf16 v[56:59], v[174:177], v[110:113], v[56:59]
	v_mfma_f32_16x16x32_bf16 v[66:69], v[162:165], v[106:109], v[66:69]
	ds_read_b128 v[162:165], v139 offset:0x200
	ds_read_b128 v[166:169], v139 offset:0x240
	v_mfma_f32_16x16x32_bf16 v[60:63], v[170:173], v[106:109], v[60:63]
	ds_read_b128 v[170:173], v139 offset:0x280
	ds_read_b128 v[174:177], v139 offset:0x2c0
	s_waitcnt lgkmcnt(0)
	v_mfma_f32_16x16x32_bf16 v[56:59], v[178:181], v[106:109], v[56:59]
	v_mul_f32_e64 v88, v88, v164
	v_mul_f32_e64 v89, v89, v165
	v_pk_mul_f32 v[86:87], v[86:87], v[162:163]
	v_pk_mul_f32 v[84:85], v[84:85], v[168:169]
	v_pk_mul_f32 v[82:83], v[82:83], v[166:167]
	v_mfma_f32_16x16x32_bf16 v[86:89], v[114:117], v[110:113], v[86:89]
	v_mul_f32_e64 v80, v80, v172
	v_mul_f32_e64 v81, v81, v173
	v_pk_mul_f32 v[78:79], v[78:79], v[170:171]
	ds_read_b128 v[114:117], v138 offset:0x6c00
	v_mfma_f32_16x16x32_bf16 v[82:85], v[122:125], v[110:113], v[82:85]
	v_mul_f32_e64 v72, v72, v176
	v_mul_f32_e64 v73, v73, v177
	v_pk_mul_f32 v[70:71], v[70:71], v[174:175]
	v_mfma_f32_16x16x32_bf16 v[78:81], v[140:143], v[110:113], v[78:81]
	v_mfma_f32_16x16x32_bf16 v[86:89], v[118:121], v[106:109], v[86:89]
	ds_read_b128 v[118:121], v138 offset:0x6c40
	ds_read_b128 v[122:125], v138 offset:0x7500
	v_mfma_f32_16x16x32_bf16 v[70:73], v[154:157], v[110:113], v[70:73]
	v_mfma_f32_16x16x32_bf16 v[82:85], v[126:129], v[106:109], v[82:85]
	ds_read_b128 v[126:129], v138 offset:0x7540
	ds_read_b128 v[140:143], v138 offset:0x7e00
	v_mfma_f32_16x16x32_bf16 v[78:81], v[144:147], v[106:109], v[78:81]
	ds_read_b128 v[144:147], v138 offset:0x7e40
	ds_read_b128 v[154:157], v138 offset:0x8700
	v_mfma_f32_16x16x32_bf16 v[70:73], v[158:161], v[106:109], v[70:73]
	ds_read_b128 v[158:161], v138 offset:0x8740
	ds_read_b128 v[162:165], v139 offset:0x300
	ds_read_b128 v[166:169], v139 offset:0x340
	ds_read_b128 v[170:173], v139 offset:0x380
	ds_read_b128 v[174:177], v139 offset:0x3c0
	s_waitcnt lgkmcnt(0)
	s_nop 0
	v_mul_f32_e64 v50, v50, v164
	v_mul_f32_e64 v51, v51, v165
	v_pk_mul_f32 v[48:49], v[48:49], v[162:163]
	v_pk_mul_f32 v[46:47], v[46:47], v[168:169]
	v_pk_mul_f32 v[44:45], v[44:45], v[166:167]
	v_pk_mul_f32 v[38:39], v[38:39], v[172:173]
	v_pk_mul_f32 v[36:37], v[36:37], v[170:171]
	v_pk_mul_f32 v[54:55], v[54:55], v[176:177]
	v_pk_mul_f32 v[52:53], v[52:53], v[174:175]
	v_mfma_f32_16x16x32_bf16 v[48:51], v[114:117], v[110:113], v[48:51]
	s_add_i32 s26, s26, 64
	s_sub_i32 s25, s25, 64
	s_add_i32 s24, s24, 1
	v_mfma_f32_16x16x32_bf16 v[44:47], v[122:125], v[110:113], v[44:47]
	s_cmpk_lg_i32 s26, 0x833
	v_mfma_f32_16x16x32_bf16 v[36:39], v[140:143], v[110:113], v[36:39]
	v_mfma_f32_16x16x32_bf16 v[52:55], v[154:157], v[110:113], v[52:55]
	v_mfma_f32_16x16x32_bf16 v[48:51], v[118:121], v[106:109], v[48:51]
	v_mfma_f32_16x16x32_bf16 v[44:47], v[126:129], v[106:109], v[44:47]
	v_mfma_f32_16x16x32_bf16 v[36:39], v[144:147], v[106:109], v[36:39]
	v_mfma_f32_16x16x32_bf16 v[52:55], v[158:161], v[106:109], v[52:55]
	s_cbranch_scc0 .LBB0_241
.LBB0_244:
	v_mov_b32_e32 v64, 0
	s_waitcnt lgkmcnt(0)
	s_barrier
	v_add_u32_e32 v108, v64, v190
	v_lshlrev_b32_e32 v106, 4, v108
	v_and_b32_e32 v64, 0x1f0, v106
	v_add_u32_e32 v110, 0, v64
	v_ashrrev_i32_e32 v64, 5, v108
	v_and_b32_e32 v107, 0x70, v106
	v_bfe_u32 v208, v108, 3, 4
	v_add_u32_e32 v208, 4, v208
	v_lshlrev_b32_e32 v208, 1, v208
	v_and_b32_e32 v208, 16, v208
	v_xor_b32_e32 v107, v107, v208
	v_mad_u64_u32 v[114:115], s[10:11], v64, s37, v[110:111]
	v_ashrrev_i32_e32 v64, 3, v108
	v_add_u32_e32 v112, s36, v107
	s_waitcnt vmcnt(17)
	ds_write_b128 v114, v[0:3]
	v_mul_lo_u32 v2, v64, s38
	v_add_u32_e32 v0, v112, v2
	v_add_u32_e32 v3, 0x200, v108
	s_waitcnt vmcnt(16)
	ds_write_b128 v0, v[4:7]
	v_ashrrev_i32_e32 v0, 5, v3
	v_mad_u64_u32 v[0:1], s[10:11], v0, s37, v[110:111]
	s_waitcnt vmcnt(15)
	ds_write_b128 v0, v[8:11]
	v_lshrrev_b32_e32 v0, 3, v3
	v_mad_u64_u32 v[0:1], s[10:11], v0, s38, v[112:113]
	v_add_u32_e32 v3, 0x400, v108
	s_waitcnt vmcnt(14)
	ds_write_b128 v0, v[12:15]
	v_ashrrev_i32_e32 v0, 5, v3
	v_mad_u64_u32 v[0:1], s[10:11], v0, s37, v[110:111]
	s_waitcnt vmcnt(13)
	ds_write_b128 v0, v[16:19]
	v_lshrrev_b32_e32 v0, 3, v3
	v_mad_u64_u32 v[0:1], s[10:11], v0, s38, v[112:113]
	v_add_u32_e32 v3, 0x600, v108
	s_waitcnt vmcnt(12)
	ds_write_b128 v0, v[20:23]
	v_ashrrev_i32_e32 v0, 5, v3
	v_mad_u64_u32 v[0:1], s[10:11], v0, s37, v[110:111]
	s_waitcnt vmcnt(11)
	ds_write_b128 v0, v[24:27]
	v_lshrrev_b32_e32 v0, 3, v3
	v_mad_u64_u32 v[0:1], s[10:11], v0, s38, v[112:113]
	s_add_i32 s27, 0, 0x1e000
	s_waitcnt vmcnt(10)
	ds_write_b128 v0, v[28:31]
	v_add3_u32 v0, s27, v2, v107
	v_cmp_gt_i32_e64 s[62:63], 64, v108
	v_ashrrev_i32_e32 v107, 31, v106
	s_waitcnt vmcnt(9)
	ds_write_b128 v0, v[32:35]
	s_and_saveexec_b64 s[10:11], s[62:63]
	s_cbranch_execz .LBB0_243
	v_add_u32_e32 v0, 0, v106
	v_add_u32_e32 v0, 0x22400, v0
	s_waitcnt vmcnt(8)
	ds_write_b128 v0, v[40:43]
	s_branch .LBB0_243
